# prologue x-pass rows re-distributed (6 per wave on the 176 workgroups that also convert weights, the rest on the other 80)
# speedup vs baseline: 1.0083x; 1.0083x over previous
; __device__ __forceinline__ unsigned cvt_pk_bf16(float lo, float hi) { unsigned r; asm volatile("v_cvt_pk_bf16_f32 %0, %1, %2" : "=v"(r) : "v"(lo), "v"(hi)); return r; }
; template <class T> __device__ __forceinline__ T* as_global(T* p) { return (T*)(GAS T*)p; }
; __device__ __forceinline__ void prologue(const Args& a, LAS unsigned char* lds, int gw, int NGW, int wave, int lane, int nlayers) {
;     ...
;     for (int m = gw; m < MTOK; m += NGW) {
;         const f32x4* xr = (const f32x4*)(as_global(a.in[0]) + (size_t)m * DM) + lane;
;         u32x2* xb = (u32x2*)((bf16_t*)(ws + WS_XB) + (size_t)m * DM) + lane;
;         float s = 0.f; f32x4 xin[4];
; #pragma unroll
;         for (int j = 0; j < 4; ++j) xin[j] = xr[64 * j];
; #pragma unroll
;         for (int j = 0; j < 4; ++j) { const f32x4 v = xin[j]; s += (v[0] * v[0] + v[1] * v[1]) + (v[2] * v[2] + v[3] * v[3]);
;             u32x2 w; w.x = cvt_pk_bf16(v[0], v[1]); w.y = cvt_pk_bf16(v[2], v[3]); xb[64 * j] = w; }
;         s = wave_sum(s);
;         if (lane == 0) stats[m] = (i64)(s * FX);
;     }
.LBB0_152:
	s_cmpk_gt_i32 s20, 0x3fff
	s_cbranch_scc1 .LBB0_157
	s_load_dwordx2 s[4:5], s[0:1], 0x0
	s_ashr_i32 s21, s20, 31
	s_ashr_i32 s23, s22, 31
	s_lshl_b64 s[6:7], s[20:21], 11
	s_lshl_b64 s[8:9], s[20:21], 3
	s_lshl_b64 s[10:11], s[22:23], 3
	v_lshl_or_b32 v2, v1, 3, s6
	v_mov_b32_e32 v3, s7
	s_lshl_b64 s[12:13], s[22:23], 11
	s_lshl_b64 s[6:7], s[20:21], 12
	s_waitcnt lgkmcnt(0)
	s_add_u32 s4, s4, s6
	v_lshlrev_b32_e32 v4, 4, v1
	v_mov_b32_e32 v5, 0
	s_addc_u32 s5, s5, s7
	v_lshl_add_u64 v[6:7], s[4:5], 0, v[4:5]
	v_mbcnt_lo_u32_b32 v4, -1, 0
	v_mbcnt_hi_u32_b32 v4, -1, v4
	s_mov_b64 s[4:5], 0xc00
	v_and_b32_e32 v8, 64, v4
	v_cmp_eq_u32_e32 vcc, 0, v1
	v_lshl_add_u64 v[6:7], v[6:7], 0, s[4:5]
	s_lshl_b64 s[14:15], s[22:23], 12
	s_mov_b32 s3, 0xa400000
	v_add_u32_e32 v8, 64, v8
	v_xor_b32_e32 v9, 1, v4
	v_xor_b32_e32 v10, 2, v4
	v_xor_b32_e32 v11, 4, v4
	v_xor_b32_e32 v12, 8, v4
	v_xor_b32_e32 v13, 16, v4
	v_xor_b32_e32 v14, 32, v4
	s_mov_b32 s6, 0x2f800000
	s_mov_b32 s7, 0xcf800000
	s_mov_b32 s18, s20
	s_movk_i32 s19, 0x3fff
	s_cmpk_lg_i32 s22, 0x800
	s_cbranch_scc1 .Lxr_single
	s_movk_i32 s19, 0x2fff

; __device__ __forceinline__ unsigned cvt_pk_bf16(float lo, float hi) { unsigned r; asm volatile("v_cvt_pk_bf16_f32 %0, %1, %2" : "=v"(r) : "v"(lo), "v"(hi)); return r; }
; template <class T> __device__ __forceinline__ T* as_global(T* p) { return (T*)(GAS T*)p; }
; __device__ __forceinline__ void prologue(const Args& a, LAS unsigned char* lds, int gw, int NGW, int wave, int lane, int nlayers) {
;     ...
;     for (int m = gw; m < MTOK; m += NGW) {
;         const f32x4* xr = (const f32x4*)(as_global(a.in[0]) + (size_t)m * DM) + lane;
;         u32x2* xb = (u32x2*)((bf16_t*)(ws + WS_XB) + (size_t)m * DM) + lane;
;         float s = 0.f; f32x4 xin[4];
; #pragma unroll
;         for (int j = 0; j < 4; ++j) xin[j] = xr[64 * j];
; #pragma unroll
;         for (int j = 0; j < 4; ++j) { const f32x4 v = xin[j]; s += (v[0] * v[0] + v[1] * v[1]) + (v[2] * v[2] + v[3] * v[3]);
;             u32x2 w; w.x = cvt_pk_bf16(v[0], v[1]); w.y = cvt_pk_bf16(v[2], v[3]); xb[64 * j] = w; }
;         s = wave_sum(s);
;         if (lane == 0) stats[m] = (i64)(s * FX);
;     }
.LBB0_154:
	s_or_b64 exec, exec, s[16:17]
	s_add_i32 s18, s18, s22
	s_add_u32 s8, s8, s10
	s_addc_u32 s9, s9, s11
	v_lshl_add_u64 v[2:3], v[2:3], 0, s[12:13]
	s_cmp_gt_i32 s18, s19
	v_lshl_add_u64 v[6:7], v[6:7], 0, s[14:15]
	s_cbranch_scc1 .Lxr_exit

; __device__ __forceinline__ unsigned cvt_pk_bf16(float lo, float hi) { unsigned r; asm volatile("v_cvt_pk_bf16_f32 %0, %1, %2" : "=v"(r) : "v"(lo), "v"(hi)); return r; }
; template <class T> __device__ __forceinline__ T* as_global(T* p) { return (T*)(GAS T*)p; }
; __device__ __forceinline__ void prologue(const Args& a, LAS unsigned char* lds, int gw, int NGW, int wave, int lane, int nlayers) {
;     ...
;     for (int m = gw; m < MTOK; m += NGW) {
;         const f32x4* xr = (const f32x4*)(as_global(a.in[0]) + (size_t)m * DM) + lane;
;         u32x2* xb = (u32x2*)((bf16_t*)(ws + WS_XB) + (size_t)m * DM) + lane;
;         float s = 0.f; f32x4 xin[4];
; #pragma unroll
;         for (int j = 0; j < 4; ++j) xin[j] = xr[64 * j];
; #pragma unroll
;         for (int j = 0; j < 4; ++j) { const f32x4 v = xin[j]; s += (v[0] * v[0] + v[1] * v[1]) + (v[2] * v[2] + v[3] * v[3]);
;             u32x2 w; w.x = cvt_pk_bf16(v[0], v[1]); w.y = cvt_pk_bf16(v[2], v[3]); xb[64 * j] = w; }
;         s = wave_sum(s);
;         if (lane == 0) stats[m] = (i64)(s * FX);
;     }
.Lxr_exit:
	s_cmpk_eq_i32 s19, 0x3fff
	s_cbranch_scc1 .LBB0_157
	s_movk_i32 s19, 0x3fff
	s_cmpk_lt_u32 s20, 0x580
	s_cbranch_scc1 .LBB0_157
	s_sub_i32 s18, s18, 0x580
	s_sub_u32 s8, s8, 0x2c00
	s_subb_u32 s9, s9, 0
	s_mov_b32 s10, 0xffd40000
	s_mov_b32 s11, -1
	v_lshl_add_u64 v[2:3], v[2:3], 0, s[10:11]
	s_mov_b32 s10, 0xffa80000
	v_lshl_add_u64 v[6:7], v[6:7], 0, s[10:11]
	s_movk_i32 s22, 0x280
	s_movk_i32 s10, 0x1400
	s_mov_b32 s11, 0
	s_mov_b32 s12, 0x140000
	s_mov_b32 s13, 0
	s_mov_b32 s14, 0x280000
	s_mov_b32 s15, 0
	s_branch .LBB0_155
